# NSA top-k: one pass over the importance row for all 8 candidates (u64 key compare) instead of 8 separate rank-count loops
# speedup vs baseline: 1.1156x; 1.0019x over previous
.LBB0_209:
	s_or_b64 exec, exec, s[4:5]
	s_cmp_lt_i32 s10, 16
	ds_write_b32 v47, v41 offset:28
	s_cselect_b64 s[62:63], -1, 0
	v_lshl_add_u32 v45, v35, 2, v203
	v_mov_b32_e32 v41, 0
	v_mov_b32_e32 v43, 0
	s_waitcnt lgkmcnt(0)
	s_barrier
	ds_read_b32 v221, v47 offset:0
	ds_read_b32 v223, v47 offset:4
	ds_read_b32 v225, v47 offset:8
	ds_read_b32 v227, v47 offset:12
	ds_read_b32 v229, v47 offset:16
	ds_read_b32 v231, v47 offset:20
	ds_read_b32 v233, v47 offset:24
	ds_read_b32 v235, v47 offset:28
	v_not_b32_e32 v220, v0
	v_add_u32_e32 v222, -1, v220
	v_add_u32_e32 v224, -2, v220
	v_add_u32_e32 v226, -3, v220
	v_add_u32_e32 v228, -4, v220
	v_add_u32_e32 v230, -5, v220
	v_add_u32_e32 v232, -6, v220
	v_add_u32_e32 v234, -7, v220
	v_mov_b32_e32 v240, 0
	v_mov_b32_e32 v241, 0
	v_mov_b32_e32 v242, 0
	v_mov_b32_e32 v243, 0
	v_mov_b32_e32 v244, 0
	v_mov_b32_e32 v245, 0
	v_mov_b32_e32 v246, 0
	v_mov_b32_e32 v247, 0
	v_add_u32_e32 v248, 0x11200, v39
	s_cmp_lt_i32 s10, 16
	s_cbranch_scc1 .Ltk_done
	s_mov_b32 s13, 1
	ds_read_b32 v237, v248 offset:4
.Ltk_loop:
	s_not_b32 s14, s13
	s_add_i32 s13, s13, 1
	v_add_u32_e32 v248, 4, v248
	v_mov_b32_e32 v238, s14
	s_waitcnt lgkmcnt(0)
	v_mov_b32_e32 v239, v237
	ds_read_b32 v237, v248 offset:4
	v_cmp_gt_u64_e64 s[38:39], v[238:239], v[220:221]
	v_cmp_gt_u64_e64 s[40:41], v[238:239], v[222:223]
	v_cmp_gt_u64_e64 s[42:43], v[238:239], v[224:225]
	v_addc_co_u32_e64 v240, s[38:39], 0, v240, s[38:39]
	v_cmp_gt_u64_e64 s[44:45], v[238:239], v[226:227]
	v_addc_co_u32_e64 v241, s[40:41], 0, v241, s[40:41]
	v_cmp_gt_u64_e64 s[46:47], v[238:239], v[228:229]
	v_addc_co_u32_e64 v242, s[42:43], 0, v242, s[42:43]
	v_cmp_gt_u64_e64 s[48:49], v[238:239], v[230:231]
	v_addc_co_u32_e64 v243, s[44:45], 0, v243, s[44:45]
	v_cmp_gt_u64_e64 s[50:51], v[238:239], v[232:233]
	v_addc_co_u32_e64 v244, s[46:47], 0, v244, s[46:47]
	v_cmp_gt_u64_e64 s[52:53], v[238:239], v[234:235]
	v_addc_co_u32_e64 v245, s[48:49], 0, v245, s[48:49]
	v_addc_co_u32_e64 v246, s[50:51], 0, v246, s[50:51]
	v_addc_co_u32_e64 v247, s[52:53], 0, v247, s[52:53]
	s_cmp_lt_i32 s13, s10
	s_cbranch_scc1 .Ltk_loop
.Ltk_done:
	s_waitcnt lgkmcnt(0)
	v_mov_b32_e32 v41, 0
	v_mov_b32_e32 v249, v0
	v_cmp_ge_i32_e64 s[4:5], s10, v249
	v_cmp_eq_u32_e64 s[6:7], 0, v249
	v_cmp_eq_u32_e64 s[14:15], s10, v249
	v_cmp_gt_u32_e64 s[16:17], 14, v240
	s_or_b64 s[6:7], s[6:7], s[14:15]
	s_or_b64 s[6:7], s[6:7], s[16:17]
	s_and_b64 s[4:5], s[4:5], s[6:7]
	v_cndmask_b32_e64 v249, 0, 1, s[4:5]
	v_lshl_or_b32 v41, v249, 0, v41
	v_add_u32_e32 v249, 1, v0
	v_cmp_ge_i32_e64 s[4:5], s10, v249
	v_cmp_eq_u32_e64 s[6:7], 0, v249
	v_cmp_eq_u32_e64 s[14:15], s10, v249
	v_cmp_gt_u32_e64 s[16:17], 14, v241
	s_or_b64 s[6:7], s[6:7], s[14:15]
	s_or_b64 s[6:7], s[6:7], s[16:17]
	s_and_b64 s[4:5], s[4:5], s[6:7]
	v_cndmask_b32_e64 v249, 0, 1, s[4:5]
	v_lshl_or_b32 v41, v249, 1, v41
	v_add_u32_e32 v249, 2, v0
	v_cmp_ge_i32_e64 s[4:5], s10, v249
	v_cmp_eq_u32_e64 s[6:7], 0, v249
	v_cmp_eq_u32_e64 s[14:15], s10, v249
	v_cmp_gt_u32_e64 s[16:17], 14, v242
	s_or_b64 s[6:7], s[6:7], s[14:15]
	s_or_b64 s[6:7], s[6:7], s[16:17]
	s_and_b64 s[4:5], s[4:5], s[6:7]
	v_cndmask_b32_e64 v249, 0, 1, s[4:5]
	v_lshl_or_b32 v41, v249, 2, v41
	v_add_u32_e32 v249, 3, v0
	v_cmp_ge_i32_e64 s[4:5], s10, v249
	v_cmp_eq_u32_e64 s[6:7], 0, v249
	v_cmp_eq_u32_e64 s[14:15], s10, v249
	v_cmp_gt_u32_e64 s[16:17], 14, v243
	s_or_b64 s[6:7], s[6:7], s[14:15]
	s_or_b64 s[6:7], s[6:7], s[16:17]
	s_and_b64 s[4:5], s[4:5], s[6:7]
	v_cndmask_b32_e64 v249, 0, 1, s[4:5]
	v_lshl_or_b32 v41, v249, 3, v41
	v_add_u32_e32 v249, 4, v0
	v_cmp_ge_i32_e64 s[4:5], s10, v249
	v_cmp_eq_u32_e64 s[6:7], 0, v249
	v_cmp_eq_u32_e64 s[14:15], s10, v249
	v_cmp_gt_u32_e64 s[16:17], 14, v244
	s_or_b64 s[6:7], s[6:7], s[14:15]
	s_or_b64 s[6:7], s[6:7], s[16:17]
	s_and_b64 s[4:5], s[4:5], s[6:7]
	v_cndmask_b32_e64 v249, 0, 1, s[4:5]
	v_lshl_or_b32 v41, v249, 4, v41
	v_add_u32_e32 v249, 5, v0
	v_cmp_ge_i32_e64 s[4:5], s10, v249
	v_cmp_eq_u32_e64 s[6:7], 0, v249
	v_cmp_eq_u32_e64 s[14:15], s10, v249
	v_cmp_gt_u32_e64 s[16:17], 14, v245
	s_or_b64 s[6:7], s[6:7], s[14:15]
	s_or_b64 s[6:7], s[6:7], s[16:17]
	s_and_b64 s[4:5], s[4:5], s[6:7]
	v_cndmask_b32_e64 v249, 0, 1, s[4:5]
	v_lshl_or_b32 v41, v249, 5, v41
	v_add_u32_e32 v249, 6, v0
	v_cmp_ge_i32_e64 s[4:5], s10, v249
	v_cmp_eq_u32_e64 s[6:7], 0, v249
	v_cmp_eq_u32_e64 s[14:15], s10, v249
	v_cmp_gt_u32_e64 s[16:17], 14, v246
	s_or_b64 s[6:7], s[6:7], s[14:15]
	s_or_b64 s[6:7], s[6:7], s[16:17]
	s_and_b64 s[4:5], s[4:5], s[6:7]
	v_cndmask_b32_e64 v249, 0, 1, s[4:5]
	v_lshl_or_b32 v41, v249, 6, v41
	v_add_u32_e32 v249, 7, v0
	v_cmp_ge_i32_e64 s[4:5], s10, v249
	v_cmp_eq_u32_e64 s[6:7], 0, v249
	v_cmp_eq_u32_e64 s[14:15], s10, v249
	v_cmp_gt_u32_e64 s[16:17], 14, v247
	s_or_b64 s[6:7], s[6:7], s[14:15]
	s_or_b64 s[6:7], s[6:7], s[16:17]
	s_and_b64 s[4:5], s[4:5], s[6:7]
	v_cndmask_b32_e64 v249, 0, 1, s[4:5]
	v_lshl_or_b32 v41, v249, 7, v41
	v_mov_b32_e32 v43, 0
	v_mov_b32_e32 v47, 0
	v_mov_b32_e32 v46, 0
	v_mov_b32_e32 v44, 0
	v_mov_b32_e32 v42, 0
	v_mov_b32_e32 v40, 0
	v_mov_b32_e32 v38, 0
	s_mov_b64 s[4:5], -1
